# M3 conv-weight LDS swizzle combined with nt hint on the P7 row loads (streaming reads)
# speedup vs baseline: 1.0027x; 1.0011x over previous
.LBB0_1188:
	s_or_b64 exec, exec, s[0:1]
	s_waitcnt lgkmcnt(0)
	v_lshrrev_b32_e32 v0, 2, v214
	v_and_b32_e32 v0, 0xf0, v0
	v_lshl_add_u32 v16, s90, 7, v0
	s_mov_b32 s0, 0x8000
	v_cmp_gt_i32_e32 vcc, s0, v16
	s_barrier
	s_and_saveexec_b64 s[0:1], vcc
	s_cbranch_execz .LBB0_1191
	v_and_b32_e32 v1, 63, v214
	v_readfirstlane_b32 s6, v214
	v_lshlrev_b32_e32 v2, 3, v1
	v_lshlrev_b32_e32 v3, 4, v1
	s_lshr_b32 s6, s6, 6
	s_lshl_b32 s7, s90, 3
	s_add_i32 s6, s6, s7
	s_lshl_b32 s6, s6, 4
	s_lshl_b32 s7, s6, 11
	s_add_u32 s2, s82, s7
	s_addc_u32 s3, s83, 0
	s_add_u32 s2, s2, 0x1800000
	s_addc_u32 s3, s3, 0
	s_lshl_b32 s7, s6, 12
	s_add_u32 s4, s80, s7
	s_addc_u32 s5, s81, 0
	global_load_dwordx4 v[4:7], v3, s[78:79]
	global_load_dwordx4 v[8:11], v3, s[78:79] offset:1024
	global_load_dwordx4 v[12:15], v3, s[78:79] offset:2048
	global_load_dwordx4 v[16:19], v3, s[78:79] offset:3072
	v_mov_b32_e32 v118, 0x358637bd
	global_load_dwordx2 v[32:33], v2, s[2:3] nt
	global_load_dwordx2 v[34:35], v2, s[2:3] offset:512 nt
	global_load_dwordx2 v[36:37], v2, s[2:3] offset:1024 nt
	global_load_dwordx2 v[38:39], v2, s[2:3] offset:1536 nt
	s_add_u32 s2, s2, 0x800
	s_addc_u32 s3, s3, 0
	global_load_dwordx2 v[40:41], v2, s[2:3] nt
	global_load_dwordx2 v[42:43], v2, s[2:3] offset:512 nt
	global_load_dwordx2 v[44:45], v2, s[2:3] offset:1024 nt
	global_load_dwordx2 v[46:47], v2, s[2:3] offset:1536 nt
	s_add_u32 s2, s2, 0x800
	s_addc_u32 s3, s3, 0
	global_load_dwordx2 v[48:49], v2, s[2:3] nt
	global_load_dwordx2 v[50:51], v2, s[2:3] offset:512 nt
	global_load_dwordx2 v[52:53], v2, s[2:3] offset:1024 nt
	global_load_dwordx2 v[54:55], v2, s[2:3] offset:1536 nt
	s_add_u32 s2, s2, 0x800
	s_addc_u32 s3, s3, 0
	global_load_dwordx2 v[56:57], v2, s[2:3] nt
	global_load_dwordx2 v[58:59], v2, s[2:3] offset:512 nt
	global_load_dwordx2 v[60:61], v2, s[2:3] offset:1024 nt
	global_load_dwordx2 v[62:63], v2, s[2:3] offset:1536 nt
	s_add_u32 s2, s2, 0x800
	s_addc_u32 s3, s3, 0
	global_load_dwordx2 v[64:65], v2, s[2:3] nt
	global_load_dwordx2 v[66:67], v2, s[2:3] offset:512 nt
	global_load_dwordx2 v[68:69], v2, s[2:3] offset:1024 nt
	global_load_dwordx2 v[70:71], v2, s[2:3] offset:1536 nt
	s_add_u32 s2, s2, 0x800
	s_addc_u32 s3, s3, 0
	global_load_dwordx2 v[72:73], v2, s[2:3] nt
	global_load_dwordx2 v[74:75], v2, s[2:3] offset:512 nt
	global_load_dwordx2 v[76:77], v2, s[2:3] offset:1024 nt
	global_load_dwordx2 v[78:79], v2, s[2:3] offset:1536 nt
	s_add_u32 s2, s2, 0x800
	s_addc_u32 s3, s3, 0
	global_load_dwordx2 v[80:81], v2, s[2:3] nt
	global_load_dwordx2 v[82:83], v2, s[2:3] offset:512 nt
	global_load_dwordx2 v[84:85], v2, s[2:3] offset:1024 nt
	global_load_dwordx2 v[86:87], v2, s[2:3] offset:1536 nt
	s_add_u32 s2, s2, 0x800
	s_addc_u32 s3, s3, 0
	global_load_dwordx2 v[88:89], v2, s[2:3] nt
	global_load_dwordx2 v[90:91], v2, s[2:3] offset:512 nt
	global_load_dwordx2 v[92:93], v2, s[2:3] offset:1024 nt
	global_load_dwordx2 v[94:95], v2, s[2:3] offset:1536 nt
	s_add_u32 s2, s2, 0x800
	s_addc_u32 s3, s3, 0
	s_waitcnt vmcnt(28)
	v_lshlrev_b32_e32 v100, 16, v32
	v_and_b32_e32 v101, 0xffff0000, v32
	v_lshlrev_b32_e32 v102, 16, v33
	v_and_b32_e32 v103, 0xffff0000, v33
	v_lshlrev_b32_e32 v104, 16, v34
	v_and_b32_e32 v105, 0xffff0000, v34
	v_lshlrev_b32_e32 v106, 16, v35
	v_and_b32_e32 v107, 0xffff0000, v35
	v_lshlrev_b32_e32 v108, 16, v36
	v_and_b32_e32 v109, 0xffff0000, v36
	v_lshlrev_b32_e32 v110, 16, v37
	v_and_b32_e32 v111, 0xffff0000, v37
	v_lshlrev_b32_e32 v112, 16, v38
	v_and_b32_e32 v113, 0xffff0000, v38
	v_lshlrev_b32_e32 v114, 16, v39
	v_and_b32_e32 v115, 0xffff0000, v39
	global_load_dwordx2 v[32:33], v2, s[2:3] nt
	global_load_dwordx2 v[34:35], v2, s[2:3] offset:512 nt
	global_load_dwordx2 v[36:37], v2, s[2:3] offset:1024 nt
	global_load_dwordx2 v[38:39], v2, s[2:3] offset:1536 nt
	s_add_u32 s2, s2, 0x800
	s_addc_u32 s3, s3, 0
	v_mul_f32_e32 v116, v100, v100
	v_fmac_f32_e32 v116, v101, v101
	v_fmac_f32_e32 v116, v102, v102
	v_fmac_f32_e32 v116, v103, v103
	v_fmac_f32_e32 v116, v104, v104
	v_fmac_f32_e32 v116, v105, v105
	v_fmac_f32_e32 v116, v106, v106
	v_fmac_f32_e32 v116, v107, v107
	v_fmac_f32_e32 v116, v108, v108
	v_fmac_f32_e32 v116, v109, v109
	v_fmac_f32_e32 v116, v110, v110
	v_fmac_f32_e32 v116, v111, v111
	v_fmac_f32_e32 v116, v112, v112
	v_fmac_f32_e32 v116, v113, v113
	v_fmac_f32_e32 v116, v114, v114
	v_fmac_f32_e32 v116, v115, v115
	s_nop 1
	v_add_f32_dpp v116, v116, v116 quad_perm:[1,0,3,2] row_mask:0xf bank_mask:0xf
	s_nop 1
	v_add_f32_dpp v116, v116, v116 quad_perm:[2,3,0,1] row_mask:0xf bank_mask:0xf
	s_nop 1
	v_add_f32_dpp v116, v116, v116 row_half_mirror row_mask:0xf bank_mask:0xf
	s_nop 1
	v_add_f32_dpp v116, v116, v116 row_mirror row_mask:0xf bank_mask:0xf
	s_nop 0
	v_readlane_b32 s8, v116, 0
	v_readlane_b32 s9, v116, 16
	v_readlane_b32 s10, v116, 32
	v_readlane_b32 s11, v116, 48
	s_nop 1
	v_mov_b32_e32 v117, s8
	v_add_f32_e32 v117, s9, v117
	v_add_f32_e32 v117, s10, v117
	v_add_f32_e32 v117, s11, v117
	v_fmamk_f32 v117, v117, 0x3a800000, v118
	v_rsq_f32_e32 v120, v117
	s_nop 0
	v_pk_mul_f32 v[100:101], v[100:101], v[120:121] op_sel_hi:[1,0]
	v_pk_mul_f32 v[102:103], v[102:103], v[120:121] op_sel_hi:[1,0]
	v_pk_mul_f32 v[104:105], v[104:105], v[120:121] op_sel_hi:[1,0]
	v_pk_mul_f32 v[106:107], v[106:107], v[120:121] op_sel_hi:[1,0]
	v_pk_mul_f32 v[108:109], v[108:109], v[120:121] op_sel_hi:[1,0]
	v_pk_mul_f32 v[110:111], v[110:111], v[120:121] op_sel_hi:[1,0]
	v_pk_mul_f32 v[112:113], v[112:113], v[120:121] op_sel_hi:[1,0]
	v_pk_mul_f32 v[114:115], v[114:115], v[120:121] op_sel_hi:[1,0]
	v_pk_mul_f32 v[100:101], v[100:101], v[4:5]
	v_pk_mul_f32 v[102:103], v[102:103], v[6:7]
	v_pk_mul_f32 v[104:105], v[104:105], v[8:9]
	v_pk_mul_f32 v[106:107], v[106:107], v[10:11]
	v_pk_mul_f32 v[108:109], v[108:109], v[12:13]
	v_pk_mul_f32 v[110:111], v[110:111], v[14:15]
	v_pk_mul_f32 v[112:113], v[112:113], v[16:17]
	v_pk_mul_f32 v[114:115], v[114:115], v[18:19]
	global_store_dwordx4 v3, v[100:103], s[4:5]
	global_store_dwordx4 v3, v[104:107], s[4:5] offset:1024
	global_store_dwordx4 v3, v[108:111], s[4:5] offset:2048
	global_store_dwordx4 v3, v[112:115], s[4:5] offset:3072
	s_add_u32 s4, s4, 0x1000
	s_addc_u32 s5, s5, 0
	s_nop 1
	s_waitcnt vmcnt(32)
	v_lshlrev_b32_e32 v100, 16, v40
	v_and_b32_e32 v101, 0xffff0000, v40
	v_lshlrev_b32_e32 v102, 16, v41
	v_and_b32_e32 v103, 0xffff0000, v41
	v_lshlrev_b32_e32 v104, 16, v42
	v_and_b32_e32 v105, 0xffff0000, v42
	v_lshlrev_b32_e32 v106, 16, v43
	v_and_b32_e32 v107, 0xffff0000, v43
	v_lshlrev_b32_e32 v108, 16, v44
	v_and_b32_e32 v109, 0xffff0000, v44
	v_lshlrev_b32_e32 v110, 16, v45
	v_and_b32_e32 v111, 0xffff0000, v45
	v_lshlrev_b32_e32 v112, 16, v46
	v_and_b32_e32 v113, 0xffff0000, v46
	v_lshlrev_b32_e32 v114, 16, v47
	v_and_b32_e32 v115, 0xffff0000, v47
	global_load_dwordx2 v[40:41], v2, s[2:3] nt
	global_load_dwordx2 v[42:43], v2, s[2:3] offset:512 nt
	global_load_dwordx2 v[44:45], v2, s[2:3] offset:1024 nt
	global_load_dwordx2 v[46:47], v2, s[2:3] offset:1536 nt
	s_add_u32 s2, s2, 0x800
	s_addc_u32 s3, s3, 0
	v_mul_f32_e32 v116, v100, v100
	v_fmac_f32_e32 v116, v101, v101
	v_fmac_f32_e32 v116, v102, v102
	v_fmac_f32_e32 v116, v103, v103
	v_fmac_f32_e32 v116, v104, v104
	v_fmac_f32_e32 v116, v105, v105
	v_fmac_f32_e32 v116, v106, v106
	v_fmac_f32_e32 v116, v107, v107
	v_fmac_f32_e32 v116, v108, v108
	v_fmac_f32_e32 v116, v109, v109
	v_fmac_f32_e32 v116, v110, v110
	v_fmac_f32_e32 v116, v111, v111
	v_fmac_f32_e32 v116, v112, v112
	v_fmac_f32_e32 v116, v113, v113
	v_fmac_f32_e32 v116, v114, v114
	v_fmac_f32_e32 v116, v115, v115
	s_nop 1
	v_add_f32_dpp v116, v116, v116 quad_perm:[1,0,3,2] row_mask:0xf bank_mask:0xf
	s_nop 1
	v_add_f32_dpp v116, v116, v116 quad_perm:[2,3,0,1] row_mask:0xf bank_mask:0xf
	s_nop 1
	v_add_f32_dpp v116, v116, v116 row_half_mirror row_mask:0xf bank_mask:0xf
	s_nop 1
	v_add_f32_dpp v116, v116, v116 row_mirror row_mask:0xf bank_mask:0xf
	s_nop 0
	v_readlane_b32 s8, v116, 0
	v_readlane_b32 s9, v116, 16
	v_readlane_b32 s10, v116, 32
	v_readlane_b32 s11, v116, 48
	s_nop 1
	v_mov_b32_e32 v117, s8
	v_add_f32_e32 v117, s9, v117
	v_add_f32_e32 v117, s10, v117
	v_add_f32_e32 v117, s11, v117
	v_fmamk_f32 v117, v117, 0x3a800000, v118
	v_rsq_f32_e32 v120, v117
	s_nop 0
	v_pk_mul_f32 v[100:101], v[100:101], v[120:121] op_sel_hi:[1,0]
	v_pk_mul_f32 v[102:103], v[102:103], v[120:121] op_sel_hi:[1,0]
	v_pk_mul_f32 v[104:105], v[104:105], v[120:121] op_sel_hi:[1,0]
	v_pk_mul_f32 v[106:107], v[106:107], v[120:121] op_sel_hi:[1,0]
	v_pk_mul_f32 v[108:109], v[108:109], v[120:121] op_sel_hi:[1,0]
	v_pk_mul_f32 v[110:111], v[110:111], v[120:121] op_sel_hi:[1,0]
	v_pk_mul_f32 v[112:113], v[112:113], v[120:121] op_sel_hi:[1,0]
	v_pk_mul_f32 v[114:115], v[114:115], v[120:121] op_sel_hi:[1,0]
	v_pk_mul_f32 v[100:101], v[100:101], v[4:5]
	v_pk_mul_f32 v[102:103], v[102:103], v[6:7]
	v_pk_mul_f32 v[104:105], v[104:105], v[8:9]
	v_pk_mul_f32 v[106:107], v[106:107], v[10:11]
	v_pk_mul_f32 v[108:109], v[108:109], v[12:13]
	v_pk_mul_f32 v[110:111], v[110:111], v[14:15]
	v_pk_mul_f32 v[112:113], v[112:113], v[16:17]
	v_pk_mul_f32 v[114:115], v[114:115], v[18:19]
	global_store_dwordx4 v3, v[100:103], s[4:5]
	global_store_dwordx4 v3, v[104:107], s[4:5] offset:1024
	global_store_dwordx4 v3, v[108:111], s[4:5] offset:2048
	global_store_dwordx4 v3, v[112:115], s[4:5] offset:3072
	s_add_u32 s4, s4, 0x1000
	s_addc_u32 s5, s5, 0
	s_nop 1
	s_waitcnt vmcnt(36)
	v_lshlrev_b32_e32 v100, 16, v48
	v_and_b32_e32 v101, 0xffff0000, v48
	v_lshlrev_b32_e32 v102, 16, v49
	v_and_b32_e32 v103, 0xffff0000, v49
	v_lshlrev_b32_e32 v104, 16, v50
	v_and_b32_e32 v105, 0xffff0000, v50
	v_lshlrev_b32_e32 v106, 16, v51
	v_and_b32_e32 v107, 0xffff0000, v51
	v_lshlrev_b32_e32 v108, 16, v52
	v_and_b32_e32 v109, 0xffff0000, v52
	v_lshlrev_b32_e32 v110, 16, v53
	v_and_b32_e32 v111, 0xffff0000, v53
	v_lshlrev_b32_e32 v112, 16, v54
	v_and_b32_e32 v113, 0xffff0000, v54
	v_lshlrev_b32_e32 v114, 16, v55
	v_and_b32_e32 v115, 0xffff0000, v55
	global_load_dwordx2 v[48:49], v2, s[2:3] nt
	global_load_dwordx2 v[50:51], v2, s[2:3] offset:512 nt
	global_load_dwordx2 v[52:53], v2, s[2:3] offset:1024 nt
	global_load_dwordx2 v[54:55], v2, s[2:3] offset:1536 nt
	s_add_u32 s2, s2, 0x800
	s_addc_u32 s3, s3, 0
	v_mul_f32_e32 v116, v100, v100
	v_fmac_f32_e32 v116, v101, v101
	v_fmac_f32_e32 v116, v102, v102
	v_fmac_f32_e32 v116, v103, v103
	v_fmac_f32_e32 v116, v104, v104
	v_fmac_f32_e32 v116, v105, v105
	v_fmac_f32_e32 v116, v106, v106
	v_fmac_f32_e32 v116, v107, v107
	v_fmac_f32_e32 v116, v108, v108
	v_fmac_f32_e32 v116, v109, v109
	v_fmac_f32_e32 v116, v110, v110
	v_fmac_f32_e32 v116, v111, v111
	v_fmac_f32_e32 v116, v112, v112
	v_fmac_f32_e32 v116, v113, v113
	v_fmac_f32_e32 v116, v114, v114
	v_fmac_f32_e32 v116, v115, v115
	s_nop 1
	v_add_f32_dpp v116, v116, v116 quad_perm:[1,0,3,2] row_mask:0xf bank_mask:0xf
	s_nop 1
	v_add_f32_dpp v116, v116, v116 quad_perm:[2,3,0,1] row_mask:0xf bank_mask:0xf
	s_nop 1
	v_add_f32_dpp v116, v116, v116 row_half_mirror row_mask:0xf bank_mask:0xf
	s_nop 1
	v_add_f32_dpp v116, v116, v116 row_mirror row_mask:0xf bank_mask:0xf
	s_nop 0
	v_readlane_b32 s8, v116, 0
	v_readlane_b32 s9, v116, 16
	v_readlane_b32 s10, v116, 32
	v_readlane_b32 s11, v116, 48
	s_nop 1
	v_mov_b32_e32 v117, s8
	v_add_f32_e32 v117, s9, v117
	v_add_f32_e32 v117, s10, v117
	v_add_f32_e32 v117, s11, v117
	v_fmamk_f32 v117, v117, 0x3a800000, v118
	v_rsq_f32_e32 v120, v117
	s_nop 0
	v_pk_mul_f32 v[100:101], v[100:101], v[120:121] op_sel_hi:[1,0]
	v_pk_mul_f32 v[102:103], v[102:103], v[120:121] op_sel_hi:[1,0]
	v_pk_mul_f32 v[104:105], v[104:105], v[120:121] op_sel_hi:[1,0]
	v_pk_mul_f32 v[106:107], v[106:107], v[120:121] op_sel_hi:[1,0]
	v_pk_mul_f32 v[108:109], v[108:109], v[120:121] op_sel_hi:[1,0]
	v_pk_mul_f32 v[110:111], v[110:111], v[120:121] op_sel_hi:[1,0]
	v_pk_mul_f32 v[112:113], v[112:113], v[120:121] op_sel_hi:[1,0]
	v_pk_mul_f32 v[114:115], v[114:115], v[120:121] op_sel_hi:[1,0]
	v_pk_mul_f32 v[100:101], v[100:101], v[4:5]
	v_pk_mul_f32 v[102:103], v[102:103], v[6:7]
	v_pk_mul_f32 v[104:105], v[104:105], v[8:9]
	v_pk_mul_f32 v[106:107], v[106:107], v[10:11]
	v_pk_mul_f32 v[108:109], v[108:109], v[12:13]
	v_pk_mul_f32 v[110:111], v[110:111], v[14:15]
	v_pk_mul_f32 v[112:113], v[112:113], v[16:17]
	v_pk_mul_f32 v[114:115], v[114:115], v[18:19]
	global_store_dwordx4 v3, v[100:103], s[4:5]
	global_store_dwordx4 v3, v[104:107], s[4:5] offset:1024
	global_store_dwordx4 v3, v[108:111], s[4:5] offset:2048
	global_store_dwordx4 v3, v[112:115], s[4:5] offset:3072
	s_add_u32 s4, s4, 0x1000
	s_addc_u32 s5, s5, 0
	s_nop 1
	s_waitcnt vmcnt(40)
	v_lshlrev_b32_e32 v100, 16, v56
	v_and_b32_e32 v101, 0xffff0000, v56
	v_lshlrev_b32_e32 v102, 16, v57
	v_and_b32_e32 v103, 0xffff0000, v57
	v_lshlrev_b32_e32 v104, 16, v58
	v_and_b32_e32 v105, 0xffff0000, v58
	v_lshlrev_b32_e32 v106, 16, v59
	v_and_b32_e32 v107, 0xffff0000, v59
	v_lshlrev_b32_e32 v108, 16, v60
	v_and_b32_e32 v109, 0xffff0000, v60
	v_lshlrev_b32_e32 v110, 16, v61
	v_and_b32_e32 v111, 0xffff0000, v61
	v_lshlrev_b32_e32 v112, 16, v62
	v_and_b32_e32 v113, 0xffff0000, v62
	v_lshlrev_b32_e32 v114, 16, v63
	v_and_b32_e32 v115, 0xffff0000, v63
	global_load_dwordx2 v[56:57], v2, s[2:3] nt
	global_load_dwordx2 v[58:59], v2, s[2:3] offset:512 nt
	global_load_dwordx2 v[60:61], v2, s[2:3] offset:1024 nt
	global_load_dwordx2 v[62:63], v2, s[2:3] offset:1536 nt
	s_add_u32 s2, s2, 0x800
	s_addc_u32 s3, s3, 0
	v_mul_f32_e32 v116, v100, v100
	v_fmac_f32_e32 v116, v101, v101
	v_fmac_f32_e32 v116, v102, v102
	v_fmac_f32_e32 v116, v103, v103
	v_fmac_f32_e32 v116, v104, v104
	v_fmac_f32_e32 v116, v105, v105
	v_fmac_f32_e32 v116, v106, v106
	v_fmac_f32_e32 v116, v107, v107
	v_fmac_f32_e32 v116, v108, v108
	v_fmac_f32_e32 v116, v109, v109
	v_fmac_f32_e32 v116, v110, v110
	v_fmac_f32_e32 v116, v111, v111
	v_fmac_f32_e32 v116, v112, v112
	v_fmac_f32_e32 v116, v113, v113
	v_fmac_f32_e32 v116, v114, v114
	v_fmac_f32_e32 v116, v115, v115
	s_nop 1
	v_add_f32_dpp v116, v116, v116 quad_perm:[1,0,3,2] row_mask:0xf bank_mask:0xf
	s_nop 1
	v_add_f32_dpp v116, v116, v116 quad_perm:[2,3,0,1] row_mask:0xf bank_mask:0xf
	s_nop 1
	v_add_f32_dpp v116, v116, v116 row_half_mirror row_mask:0xf bank_mask:0xf
	s_nop 1
	v_add_f32_dpp v116, v116, v116 row_mirror row_mask:0xf bank_mask:0xf
	s_nop 0
	v_readlane_b32 s8, v116, 0
	v_readlane_b32 s9, v116, 16
	v_readlane_b32 s10, v116, 32
	v_readlane_b32 s11, v116, 48
	s_nop 1
	v_mov_b32_e32 v117, s8
	v_add_f32_e32 v117, s9, v117
	v_add_f32_e32 v117, s10, v117
	v_add_f32_e32 v117, s11, v117
	v_fmamk_f32 v117, v117, 0x3a800000, v118
	v_rsq_f32_e32 v120, v117
	s_nop 0
	v_pk_mul_f32 v[100:101], v[100:101], v[120:121] op_sel_hi:[1,0]
	v_pk_mul_f32 v[102:103], v[102:103], v[120:121] op_sel_hi:[1,0]
	v_pk_mul_f32 v[104:105], v[104:105], v[120:121] op_sel_hi:[1,0]
	v_pk_mul_f32 v[106:107], v[106:107], v[120:121] op_sel_hi:[1,0]
	v_pk_mul_f32 v[108:109], v[108:109], v[120:121] op_sel_hi:[1,0]
	v_pk_mul_f32 v[110:111], v[110:111], v[120:121] op_sel_hi:[1,0]
	v_pk_mul_f32 v[112:113], v[112:113], v[120:121] op_sel_hi:[1,0]
	v_pk_mul_f32 v[114:115], v[114:115], v[120:121] op_sel_hi:[1,0]
	v_pk_mul_f32 v[100:101], v[100:101], v[4:5]
	v_pk_mul_f32 v[102:103], v[102:103], v[6:7]
	v_pk_mul_f32 v[104:105], v[104:105], v[8:9]
	v_pk_mul_f32 v[106:107], v[106:107], v[10:11]
	v_pk_mul_f32 v[108:109], v[108:109], v[12:13]
	v_pk_mul_f32 v[110:111], v[110:111], v[14:15]
	v_pk_mul_f32 v[112:113], v[112:113], v[16:17]
	v_pk_mul_f32 v[114:115], v[114:115], v[18:19]
	global_store_dwordx4 v3, v[100:103], s[4:5]
	global_store_dwordx4 v3, v[104:107], s[4:5] offset:1024
	global_store_dwordx4 v3, v[108:111], s[4:5] offset:2048
	global_store_dwordx4 v3, v[112:115], s[4:5] offset:3072
	s_add_u32 s4, s4, 0x1000
	s_addc_u32 s5, s5, 0
	s_nop 1
	s_waitcnt vmcnt(44)
	v_lshlrev_b32_e32 v100, 16, v64
	v_and_b32_e32 v101, 0xffff0000, v64
	v_lshlrev_b32_e32 v102, 16, v65
	v_and_b32_e32 v103, 0xffff0000, v65
	v_lshlrev_b32_e32 v104, 16, v66
	v_and_b32_e32 v105, 0xffff0000, v66
	v_lshlrev_b32_e32 v106, 16, v67
	v_and_b32_e32 v107, 0xffff0000, v67
	v_lshlrev_b32_e32 v108, 16, v68
	v_and_b32_e32 v109, 0xffff0000, v68
	v_lshlrev_b32_e32 v110, 16, v69
	v_and_b32_e32 v111, 0xffff0000, v69
	v_lshlrev_b32_e32 v112, 16, v70
	v_and_b32_e32 v113, 0xffff0000, v70
	v_lshlrev_b32_e32 v114, 16, v71
	v_and_b32_e32 v115, 0xffff0000, v71
	global_load_dwordx2 v[64:65], v2, s[2:3] nt
	global_load_dwordx2 v[66:67], v2, s[2:3] offset:512 nt
	global_load_dwordx2 v[68:69], v2, s[2:3] offset:1024 nt
	global_load_dwordx2 v[70:71], v2, s[2:3] offset:1536 nt
	s_add_u32 s2, s2, 0x800
	s_addc_u32 s3, s3, 0
	v_mul_f32_e32 v116, v100, v100
	v_fmac_f32_e32 v116, v101, v101
	v_fmac_f32_e32 v116, v102, v102
	v_fmac_f32_e32 v116, v103, v103
	v_fmac_f32_e32 v116, v104, v104
	v_fmac_f32_e32 v116, v105, v105
	v_fmac_f32_e32 v116, v106, v106
	v_fmac_f32_e32 v116, v107, v107
	v_fmac_f32_e32 v116, v108, v108
	v_fmac_f32_e32 v116, v109, v109
	v_fmac_f32_e32 v116, v110, v110
	v_fmac_f32_e32 v116, v111, v111
	v_fmac_f32_e32 v116, v112, v112
	v_fmac_f32_e32 v116, v113, v113
	v_fmac_f32_e32 v116, v114, v114
	v_fmac_f32_e32 v116, v115, v115
	s_nop 1
	v_add_f32_dpp v116, v116, v116 quad_perm:[1,0,3,2] row_mask:0xf bank_mask:0xf
	s_nop 1
	v_add_f32_dpp v116, v116, v116 quad_perm:[2,3,0,1] row_mask:0xf bank_mask:0xf
	s_nop 1
	v_add_f32_dpp v116, v116, v116 row_half_mirror row_mask:0xf bank_mask:0xf
	s_nop 1
	v_add_f32_dpp v116, v116, v116 row_mirror row_mask:0xf bank_mask:0xf
	s_nop 0
	v_readlane_b32 s8, v116, 0
	v_readlane_b32 s9, v116, 16
	v_readlane_b32 s10, v116, 32
	v_readlane_b32 s11, v116, 48
	s_nop 1
	v_mov_b32_e32 v117, s8
	v_add_f32_e32 v117, s9, v117
	v_add_f32_e32 v117, s10, v117
	v_add_f32_e32 v117, s11, v117
	v_fmamk_f32 v117, v117, 0x3a800000, v118
	v_rsq_f32_e32 v120, v117
	s_nop 0
	v_pk_mul_f32 v[100:101], v[100:101], v[120:121] op_sel_hi:[1,0]
	v_pk_mul_f32 v[102:103], v[102:103], v[120:121] op_sel_hi:[1,0]
	v_pk_mul_f32 v[104:105], v[104:105], v[120:121] op_sel_hi:[1,0]
	v_pk_mul_f32 v[106:107], v[106:107], v[120:121] op_sel_hi:[1,0]
	v_pk_mul_f32 v[108:109], v[108:109], v[120:121] op_sel_hi:[1,0]
	v_pk_mul_f32 v[110:111], v[110:111], v[120:121] op_sel_hi:[1,0]
	v_pk_mul_f32 v[112:113], v[112:113], v[120:121] op_sel_hi:[1,0]
	v_pk_mul_f32 v[114:115], v[114:115], v[120:121] op_sel_hi:[1,0]
	v_pk_mul_f32 v[100:101], v[100:101], v[4:5]
	v_pk_mul_f32 v[102:103], v[102:103], v[6:7]
	v_pk_mul_f32 v[104:105], v[104:105], v[8:9]
	v_pk_mul_f32 v[106:107], v[106:107], v[10:11]
	v_pk_mul_f32 v[108:109], v[108:109], v[12:13]
	v_pk_mul_f32 v[110:111], v[110:111], v[14:15]
	v_pk_mul_f32 v[112:113], v[112:113], v[16:17]
	v_pk_mul_f32 v[114:115], v[114:115], v[18:19]
	global_store_dwordx4 v3, v[100:103], s[4:5]
	global_store_dwordx4 v3, v[104:107], s[4:5] offset:1024
	global_store_dwordx4 v3, v[108:111], s[4:5] offset:2048
	global_store_dwordx4 v3, v[112:115], s[4:5] offset:3072
	s_add_u32 s4, s4, 0x1000
	s_addc_u32 s5, s5, 0
	s_nop 1
	s_waitcnt vmcnt(48)
	v_lshlrev_b32_e32 v100, 16, v72
	v_and_b32_e32 v101, 0xffff0000, v72
	v_lshlrev_b32_e32 v102, 16, v73
	v_and_b32_e32 v103, 0xffff0000, v73
	v_lshlrev_b32_e32 v104, 16, v74
	v_and_b32_e32 v105, 0xffff0000, v74
	v_lshlrev_b32_e32 v106, 16, v75
	v_and_b32_e32 v107, 0xffff0000, v75
	v_lshlrev_b32_e32 v108, 16, v76
	v_and_b32_e32 v109, 0xffff0000, v76
	v_lshlrev_b32_e32 v110, 16, v77
	v_and_b32_e32 v111, 0xffff0000, v77
	v_lshlrev_b32_e32 v112, 16, v78
	v_and_b32_e32 v113, 0xffff0000, v78
	v_lshlrev_b32_e32 v114, 16, v79
	v_and_b32_e32 v115, 0xffff0000, v79
	global_load_dwordx2 v[72:73], v2, s[2:3] nt
	global_load_dwordx2 v[74:75], v2, s[2:3] offset:512 nt
	global_load_dwordx2 v[76:77], v2, s[2:3] offset:1024 nt
	global_load_dwordx2 v[78:79], v2, s[2:3] offset:1536 nt
	s_add_u32 s2, s2, 0x800
	s_addc_u32 s3, s3, 0
	v_mul_f32_e32 v116, v100, v100
	v_fmac_f32_e32 v116, v101, v101
	v_fmac_f32_e32 v116, v102, v102
	v_fmac_f32_e32 v116, v103, v103
	v_fmac_f32_e32 v116, v104, v104
	v_fmac_f32_e32 v116, v105, v105
	v_fmac_f32_e32 v116, v106, v106
	v_fmac_f32_e32 v116, v107, v107
	v_fmac_f32_e32 v116, v108, v108
	v_fmac_f32_e32 v116, v109, v109
	v_fmac_f32_e32 v116, v110, v110
	v_fmac_f32_e32 v116, v111, v111
	v_fmac_f32_e32 v116, v112, v112
	v_fmac_f32_e32 v116, v113, v113
	v_fmac_f32_e32 v116, v114, v114
	v_fmac_f32_e32 v116, v115, v115
	s_nop 1
	v_add_f32_dpp v116, v116, v116 quad_perm:[1,0,3,2] row_mask:0xf bank_mask:0xf
	s_nop 1
	v_add_f32_dpp v116, v116, v116 quad_perm:[2,3,0,1] row_mask:0xf bank_mask:0xf
	s_nop 1
	v_add_f32_dpp v116, v116, v116 row_half_mirror row_mask:0xf bank_mask:0xf
	s_nop 1
	v_add_f32_dpp v116, v116, v116 row_mirror row_mask:0xf bank_mask:0xf
	s_nop 0
	v_readlane_b32 s8, v116, 0
	v_readlane_b32 s9, v116, 16
	v_readlane_b32 s10, v116, 32
	v_readlane_b32 s11, v116, 48
	s_nop 1
	v_mov_b32_e32 v117, s8
	v_add_f32_e32 v117, s9, v117
	v_add_f32_e32 v117, s10, v117
	v_add_f32_e32 v117, s11, v117
	v_fmamk_f32 v117, v117, 0x3a800000, v118
	v_rsq_f32_e32 v120, v117
	s_nop 0
	v_pk_mul_f32 v[100:101], v[100:101], v[120:121] op_sel_hi:[1,0]
	v_pk_mul_f32 v[102:103], v[102:103], v[120:121] op_sel_hi:[1,0]
	v_pk_mul_f32 v[104:105], v[104:105], v[120:121] op_sel_hi:[1,0]
	v_pk_mul_f32 v[106:107], v[106:107], v[120:121] op_sel_hi:[1,0]
	v_pk_mul_f32 v[108:109], v[108:109], v[120:121] op_sel_hi:[1,0]
	v_pk_mul_f32 v[110:111], v[110:111], v[120:121] op_sel_hi:[1,0]
	v_pk_mul_f32 v[112:113], v[112:113], v[120:121] op_sel_hi:[1,0]
	v_pk_mul_f32 v[114:115], v[114:115], v[120:121] op_sel_hi:[1,0]
	v_pk_mul_f32 v[100:101], v[100:101], v[4:5]
	v_pk_mul_f32 v[102:103], v[102:103], v[6:7]
	v_pk_mul_f32 v[104:105], v[104:105], v[8:9]
	v_pk_mul_f32 v[106:107], v[106:107], v[10:11]
	v_pk_mul_f32 v[108:109], v[108:109], v[12:13]
	v_pk_mul_f32 v[110:111], v[110:111], v[14:15]
	v_pk_mul_f32 v[112:113], v[112:113], v[16:17]
	v_pk_mul_f32 v[114:115], v[114:115], v[18:19]
	global_store_dwordx4 v3, v[100:103], s[4:5]
	global_store_dwordx4 v3, v[104:107], s[4:5] offset:1024
	global_store_dwordx4 v3, v[108:111], s[4:5] offset:2048
	global_store_dwordx4 v3, v[112:115], s[4:5] offset:3072
	s_add_u32 s4, s4, 0x1000
	s_addc_u32 s5, s5, 0
	s_nop 1
	s_waitcnt vmcnt(52)
	v_lshlrev_b32_e32 v100, 16, v80
	v_and_b32_e32 v101, 0xffff0000, v80
	v_lshlrev_b32_e32 v102, 16, v81
	v_and_b32_e32 v103, 0xffff0000, v81
	v_lshlrev_b32_e32 v104, 16, v82
	v_and_b32_e32 v105, 0xffff0000, v82
	v_lshlrev_b32_e32 v106, 16, v83
	v_and_b32_e32 v107, 0xffff0000, v83
	v_lshlrev_b32_e32 v108, 16, v84
	v_and_b32_e32 v109, 0xffff0000, v84
	v_lshlrev_b32_e32 v110, 16, v85
	v_and_b32_e32 v111, 0xffff0000, v85
	v_lshlrev_b32_e32 v112, 16, v86
	v_and_b32_e32 v113, 0xffff0000, v86
	v_lshlrev_b32_e32 v114, 16, v87
	v_and_b32_e32 v115, 0xffff0000, v87
	global_load_dwordx2 v[80:81], v2, s[2:3] nt
	global_load_dwordx2 v[82:83], v2, s[2:3] offset:512 nt
	global_load_dwordx2 v[84:85], v2, s[2:3] offset:1024 nt
	global_load_dwordx2 v[86:87], v2, s[2:3] offset:1536 nt
	s_add_u32 s2, s2, 0x800
	s_addc_u32 s3, s3, 0
	v_mul_f32_e32 v116, v100, v100
	v_fmac_f32_e32 v116, v101, v101
	v_fmac_f32_e32 v116, v102, v102
	v_fmac_f32_e32 v116, v103, v103
	v_fmac_f32_e32 v116, v104, v104
	v_fmac_f32_e32 v116, v105, v105
	v_fmac_f32_e32 v116, v106, v106
	v_fmac_f32_e32 v116, v107, v107
	v_fmac_f32_e32 v116, v108, v108
	v_fmac_f32_e32 v116, v109, v109
	v_fmac_f32_e32 v116, v110, v110
	v_fmac_f32_e32 v116, v111, v111
	v_fmac_f32_e32 v116, v112, v112
	v_fmac_f32_e32 v116, v113, v113
	v_fmac_f32_e32 v116, v114, v114
	v_fmac_f32_e32 v116, v115, v115
	s_nop 1
	v_add_f32_dpp v116, v116, v116 quad_perm:[1,0,3,2] row_mask:0xf bank_mask:0xf
	s_nop 1
	v_add_f32_dpp v116, v116, v116 quad_perm:[2,3,0,1] row_mask:0xf bank_mask:0xf
	s_nop 1
	v_add_f32_dpp v116, v116, v116 row_half_mirror row_mask:0xf bank_mask:0xf
	s_nop 1
	v_add_f32_dpp v116, v116, v116 row_mirror row_mask:0xf bank_mask:0xf
	s_nop 0
	v_readlane_b32 s8, v116, 0
	v_readlane_b32 s9, v116, 16
	v_readlane_b32 s10, v116, 32
	v_readlane_b32 s11, v116, 48
	s_nop 1
	v_mov_b32_e32 v117, s8
	v_add_f32_e32 v117, s9, v117
	v_add_f32_e32 v117, s10, v117
	v_add_f32_e32 v117, s11, v117
	v_fmamk_f32 v117, v117, 0x3a800000, v118
	v_rsq_f32_e32 v120, v117
	s_nop 0
	v_pk_mul_f32 v[100:101], v[100:101], v[120:121] op_sel_hi:[1,0]
	v_pk_mul_f32 v[102:103], v[102:103], v[120:121] op_sel_hi:[1,0]
	v_pk_mul_f32 v[104:105], v[104:105], v[120:121] op_sel_hi:[1,0]
	v_pk_mul_f32 v[106:107], v[106:107], v[120:121] op_sel_hi:[1,0]
	v_pk_mul_f32 v[108:109], v[108:109], v[120:121] op_sel_hi:[1,0]
	v_pk_mul_f32 v[110:111], v[110:111], v[120:121] op_sel_hi:[1,0]
	v_pk_mul_f32 v[112:113], v[112:113], v[120:121] op_sel_hi:[1,0]
	v_pk_mul_f32 v[114:115], v[114:115], v[120:121] op_sel_hi:[1,0]
	v_pk_mul_f32 v[100:101], v[100:101], v[4:5]
	v_pk_mul_f32 v[102:103], v[102:103], v[6:7]
	v_pk_mul_f32 v[104:105], v[104:105], v[8:9]
	v_pk_mul_f32 v[106:107], v[106:107], v[10:11]
	v_pk_mul_f32 v[108:109], v[108:109], v[12:13]
	v_pk_mul_f32 v[110:111], v[110:111], v[14:15]
	v_pk_mul_f32 v[112:113], v[112:113], v[16:17]
	v_pk_mul_f32 v[114:115], v[114:115], v[18:19]
	global_store_dwordx4 v3, v[100:103], s[4:5]
	global_store_dwordx4 v3, v[104:107], s[4:5] offset:1024
	global_store_dwordx4 v3, v[108:111], s[4:5] offset:2048
	global_store_dwordx4 v3, v[112:115], s[4:5] offset:3072
	s_add_u32 s4, s4, 0x1000
	s_addc_u32 s5, s5, 0
	s_nop 1
	s_waitcnt vmcnt(56)
	v_lshlrev_b32_e32 v100, 16, v88
	v_and_b32_e32 v101, 0xffff0000, v88
	v_lshlrev_b32_e32 v102, 16, v89
	v_and_b32_e32 v103, 0xffff0000, v89
	v_lshlrev_b32_e32 v104, 16, v90
	v_and_b32_e32 v105, 0xffff0000, v90
	v_lshlrev_b32_e32 v106, 16, v91
	v_and_b32_e32 v107, 0xffff0000, v91
	v_lshlrev_b32_e32 v108, 16, v92
	v_and_b32_e32 v109, 0xffff0000, v92
	v_lshlrev_b32_e32 v110, 16, v93
	v_and_b32_e32 v111, 0xffff0000, v93
	v_lshlrev_b32_e32 v112, 16, v94
	v_and_b32_e32 v113, 0xffff0000, v94
	v_lshlrev_b32_e32 v114, 16, v95
	v_and_b32_e32 v115, 0xffff0000, v95
	global_load_dwordx2 v[88:89], v2, s[2:3] nt
	global_load_dwordx2 v[90:91], v2, s[2:3] offset:512 nt
	global_load_dwordx2 v[92:93], v2, s[2:3] offset:1024 nt
	global_load_dwordx2 v[94:95], v2, s[2:3] offset:1536 nt
	s_add_u32 s2, s2, 0x800
	s_addc_u32 s3, s3, 0
	v_mul_f32_e32 v116, v100, v100
	v_fmac_f32_e32 v116, v101, v101
	v_fmac_f32_e32 v116, v102, v102
	v_fmac_f32_e32 v116, v103, v103
	v_fmac_f32_e32 v116, v104, v104
	v_fmac_f32_e32 v116, v105, v105
	v_fmac_f32_e32 v116, v106, v106
	v_fmac_f32_e32 v116, v107, v107
	v_fmac_f32_e32 v116, v108, v108
	v_fmac_f32_e32 v116, v109, v109
	v_fmac_f32_e32 v116, v110, v110
	v_fmac_f32_e32 v116, v111, v111
	v_fmac_f32_e32 v116, v112, v112
	v_fmac_f32_e32 v116, v113, v113
	v_fmac_f32_e32 v116, v114, v114
	v_fmac_f32_e32 v116, v115, v115
	s_nop 1
	v_add_f32_dpp v116, v116, v116 quad_perm:[1,0,3,2] row_mask:0xf bank_mask:0xf
	s_nop 1
	v_add_f32_dpp v116, v116, v116 quad_perm:[2,3,0,1] row_mask:0xf bank_mask:0xf
	s_nop 1
	v_add_f32_dpp v116, v116, v116 row_half_mirror row_mask:0xf bank_mask:0xf
	s_nop 1
	v_add_f32_dpp v116, v116, v116 row_mirror row_mask:0xf bank_mask:0xf
	s_nop 0
	v_readlane_b32 s8, v116, 0
	v_readlane_b32 s9, v116, 16
	v_readlane_b32 s10, v116, 32
	v_readlane_b32 s11, v116, 48
	s_nop 1
	v_mov_b32_e32 v117, s8
	v_add_f32_e32 v117, s9, v117
	v_add_f32_e32 v117, s10, v117
	v_add_f32_e32 v117, s11, v117
	v_fmamk_f32 v117, v117, 0x3a800000, v118
	v_rsq_f32_e32 v120, v117
	s_nop 0
	v_pk_mul_f32 v[100:101], v[100:101], v[120:121] op_sel_hi:[1,0]
	v_pk_mul_f32 v[102:103], v[102:103], v[120:121] op_sel_hi:[1,0]
	v_pk_mul_f32 v[104:105], v[104:105], v[120:121] op_sel_hi:[1,0]
	v_pk_mul_f32 v[106:107], v[106:107], v[120:121] op_sel_hi:[1,0]
	v_pk_mul_f32 v[108:109], v[108:109], v[120:121] op_sel_hi:[1,0]
	v_pk_mul_f32 v[110:111], v[110:111], v[120:121] op_sel_hi:[1,0]
	v_pk_mul_f32 v[112:113], v[112:113], v[120:121] op_sel_hi:[1,0]
	v_pk_mul_f32 v[114:115], v[114:115], v[120:121] op_sel_hi:[1,0]
	v_pk_mul_f32 v[100:101], v[100:101], v[4:5]
	v_pk_mul_f32 v[102:103], v[102:103], v[6:7]
	v_pk_mul_f32 v[104:105], v[104:105], v[8:9]
	v_pk_mul_f32 v[106:107], v[106:107], v[10:11]
	v_pk_mul_f32 v[108:109], v[108:109], v[12:13]
	v_pk_mul_f32 v[110:111], v[110:111], v[14:15]
	v_pk_mul_f32 v[112:113], v[112:113], v[16:17]
	v_pk_mul_f32 v[114:115], v[114:115], v[18:19]
	global_store_dwordx4 v3, v[100:103], s[4:5]
	global_store_dwordx4 v3, v[104:107], s[4:5] offset:1024
	global_store_dwordx4 v3, v[108:111], s[4:5] offset:2048
	global_store_dwordx4 v3, v[112:115], s[4:5] offset:3072
	s_add_u32 s4, s4, 0x1000
	s_addc_u32 s5, s5, 0
	s_nop 1
	s_waitcnt vmcnt(60)
	v_lshlrev_b32_e32 v100, 16, v32
	v_and_b32_e32 v101, 0xffff0000, v32
	v_lshlrev_b32_e32 v102, 16, v33
	v_and_b32_e32 v103, 0xffff0000, v33
	v_lshlrev_b32_e32 v104, 16, v34
	v_and_b32_e32 v105, 0xffff0000, v34
	v_lshlrev_b32_e32 v106, 16, v35
	v_and_b32_e32 v107, 0xffff0000, v35
	v_lshlrev_b32_e32 v108, 16, v36
	v_and_b32_e32 v109, 0xffff0000, v36
	v_lshlrev_b32_e32 v110, 16, v37
	v_and_b32_e32 v111, 0xffff0000, v37
	v_lshlrev_b32_e32 v112, 16, v38
	v_and_b32_e32 v113, 0xffff0000, v38
	v_lshlrev_b32_e32 v114, 16, v39
	v_and_b32_e32 v115, 0xffff0000, v39
	v_mul_f32_e32 v116, v100, v100
	v_fmac_f32_e32 v116, v101, v101
	v_fmac_f32_e32 v116, v102, v102
	v_fmac_f32_e32 v116, v103, v103
	v_fmac_f32_e32 v116, v104, v104
	v_fmac_f32_e32 v116, v105, v105
	v_fmac_f32_e32 v116, v106, v106
	v_fmac_f32_e32 v116, v107, v107
	v_fmac_f32_e32 v116, v108, v108
	v_fmac_f32_e32 v116, v109, v109
	v_fmac_f32_e32 v116, v110, v110
	v_fmac_f32_e32 v116, v111, v111
	v_fmac_f32_e32 v116, v112, v112
	v_fmac_f32_e32 v116, v113, v113
	v_fmac_f32_e32 v116, v114, v114
	v_fmac_f32_e32 v116, v115, v115
	s_nop 1
	v_add_f32_dpp v116, v116, v116 quad_perm:[1,0,3,2] row_mask:0xf bank_mask:0xf
	s_nop 1
	v_add_f32_dpp v116, v116, v116 quad_perm:[2,3,0,1] row_mask:0xf bank_mask:0xf
	s_nop 1
	v_add_f32_dpp v116, v116, v116 row_half_mirror row_mask:0xf bank_mask:0xf
	s_nop 1
	v_add_f32_dpp v116, v116, v116 row_mirror row_mask:0xf bank_mask:0xf
	s_nop 0
	v_readlane_b32 s8, v116, 0
	v_readlane_b32 s9, v116, 16
	v_readlane_b32 s10, v116, 32
	v_readlane_b32 s11, v116, 48
	s_nop 1
	v_mov_b32_e32 v117, s8
	v_add_f32_e32 v117, s9, v117
	v_add_f32_e32 v117, s10, v117
	v_add_f32_e32 v117, s11, v117
	v_fmamk_f32 v117, v117, 0x3a800000, v118
	v_rsq_f32_e32 v120, v117
	s_nop 0
	v_pk_mul_f32 v[100:101], v[100:101], v[120:121] op_sel_hi:[1,0]
	v_pk_mul_f32 v[102:103], v[102:103], v[120:121] op_sel_hi:[1,0]
	v_pk_mul_f32 v[104:105], v[104:105], v[120:121] op_sel_hi:[1,0]
	v_pk_mul_f32 v[106:107], v[106:107], v[120:121] op_sel_hi:[1,0]
	v_pk_mul_f32 v[108:109], v[108:109], v[120:121] op_sel_hi:[1,0]
	v_pk_mul_f32 v[110:111], v[110:111], v[120:121] op_sel_hi:[1,0]
	v_pk_mul_f32 v[112:113], v[112:113], v[120:121] op_sel_hi:[1,0]
	v_pk_mul_f32 v[114:115], v[114:115], v[120:121] op_sel_hi:[1,0]
	v_pk_mul_f32 v[100:101], v[100:101], v[4:5]
	v_pk_mul_f32 v[102:103], v[102:103], v[6:7]
	v_pk_mul_f32 v[104:105], v[104:105], v[8:9]
	v_pk_mul_f32 v[106:107], v[106:107], v[10:11]
	v_pk_mul_f32 v[108:109], v[108:109], v[12:13]
	v_pk_mul_f32 v[110:111], v[110:111], v[14:15]
	v_pk_mul_f32 v[112:113], v[112:113], v[16:17]
	v_pk_mul_f32 v[114:115], v[114:115], v[18:19]
	global_store_dwordx4 v3, v[100:103], s[4:5]
	global_store_dwordx4 v3, v[104:107], s[4:5] offset:1024
	global_store_dwordx4 v3, v[108:111], s[4:5] offset:2048
	global_store_dwordx4 v3, v[112:115], s[4:5] offset:3072
	s_add_u32 s4, s4, 0x1000
	s_addc_u32 s5, s5, 0
	s_nop 1
	s_waitcnt vmcnt(56)
	v_lshlrev_b32_e32 v100, 16, v40
	v_and_b32_e32 v101, 0xffff0000, v40
	v_lshlrev_b32_e32 v102, 16, v41
	v_and_b32_e32 v103, 0xffff0000, v41
	v_lshlrev_b32_e32 v104, 16, v42
	v_and_b32_e32 v105, 0xffff0000, v42
	v_lshlrev_b32_e32 v106, 16, v43
	v_and_b32_e32 v107, 0xffff0000, v43
	v_lshlrev_b32_e32 v108, 16, v44
	v_and_b32_e32 v109, 0xffff0000, v44
	v_lshlrev_b32_e32 v110, 16, v45
	v_and_b32_e32 v111, 0xffff0000, v45
	v_lshlrev_b32_e32 v112, 16, v46
	v_and_b32_e32 v113, 0xffff0000, v46
	v_lshlrev_b32_e32 v114, 16, v47
	v_and_b32_e32 v115, 0xffff0000, v47
	v_mul_f32_e32 v116, v100, v100
	v_fmac_f32_e32 v116, v101, v101
	v_fmac_f32_e32 v116, v102, v102
	v_fmac_f32_e32 v116, v103, v103
	v_fmac_f32_e32 v116, v104, v104
	v_fmac_f32_e32 v116, v105, v105
	v_fmac_f32_e32 v116, v106, v106
	v_fmac_f32_e32 v116, v107, v107
	v_fmac_f32_e32 v116, v108, v108
	v_fmac_f32_e32 v116, v109, v109
	v_fmac_f32_e32 v116, v110, v110
	v_fmac_f32_e32 v116, v111, v111
	v_fmac_f32_e32 v116, v112, v112
	v_fmac_f32_e32 v116, v113, v113
	v_fmac_f32_e32 v116, v114, v114
	v_fmac_f32_e32 v116, v115, v115
	s_nop 1
	v_add_f32_dpp v116, v116, v116 quad_perm:[1,0,3,2] row_mask:0xf bank_mask:0xf
	s_nop 1
	v_add_f32_dpp v116, v116, v116 quad_perm:[2,3,0,1] row_mask:0xf bank_mask:0xf
	s_nop 1
	v_add_f32_dpp v116, v116, v116 row_half_mirror row_mask:0xf bank_mask:0xf
	s_nop 1
	v_add_f32_dpp v116, v116, v116 row_mirror row_mask:0xf bank_mask:0xf
	s_nop 0
	v_readlane_b32 s8, v116, 0
	v_readlane_b32 s9, v116, 16
	v_readlane_b32 s10, v116, 32
	v_readlane_b32 s11, v116, 48
	s_nop 1
	v_mov_b32_e32 v117, s8
	v_add_f32_e32 v117, s9, v117
	v_add_f32_e32 v117, s10, v117
	v_add_f32_e32 v117, s11, v117
	v_fmamk_f32 v117, v117, 0x3a800000, v118
	v_rsq_f32_e32 v120, v117
	s_nop 0
	v_pk_mul_f32 v[100:101], v[100:101], v[120:121] op_sel_hi:[1,0]
	v_pk_mul_f32 v[102:103], v[102:103], v[120:121] op_sel_hi:[1,0]
	v_pk_mul_f32 v[104:105], v[104:105], v[120:121] op_sel_hi:[1,0]
	v_pk_mul_f32 v[106:107], v[106:107], v[120:121] op_sel_hi:[1,0]
	v_pk_mul_f32 v[108:109], v[108:109], v[120:121] op_sel_hi:[1,0]
	v_pk_mul_f32 v[110:111], v[110:111], v[120:121] op_sel_hi:[1,0]
	v_pk_mul_f32 v[112:113], v[112:113], v[120:121] op_sel_hi:[1,0]
	v_pk_mul_f32 v[114:115], v[114:115], v[120:121] op_sel_hi:[1,0]
	v_pk_mul_f32 v[100:101], v[100:101], v[4:5]
	v_pk_mul_f32 v[102:103], v[102:103], v[6:7]
	v_pk_mul_f32 v[104:105], v[104:105], v[8:9]
	v_pk_mul_f32 v[106:107], v[106:107], v[10:11]
	v_pk_mul_f32 v[108:109], v[108:109], v[12:13]
	v_pk_mul_f32 v[110:111], v[110:111], v[14:15]
	v_pk_mul_f32 v[112:113], v[112:113], v[16:17]
	v_pk_mul_f32 v[114:115], v[114:115], v[18:19]
	global_store_dwordx4 v3, v[100:103], s[4:5]
	global_store_dwordx4 v3, v[104:107], s[4:5] offset:1024
	global_store_dwordx4 v3, v[108:111], s[4:5] offset:2048
	global_store_dwordx4 v3, v[112:115], s[4:5] offset:3072
	s_add_u32 s4, s4, 0x1000
	s_addc_u32 s5, s5, 0
	s_nop 1
	s_waitcnt vmcnt(52)
	v_lshlrev_b32_e32 v100, 16, v48
	v_and_b32_e32 v101, 0xffff0000, v48
	v_lshlrev_b32_e32 v102, 16, v49
	v_and_b32_e32 v103, 0xffff0000, v49
	v_lshlrev_b32_e32 v104, 16, v50
	v_and_b32_e32 v105, 0xffff0000, v50
	v_lshlrev_b32_e32 v106, 16, v51
	v_and_b32_e32 v107, 0xffff0000, v51
	v_lshlrev_b32_e32 v108, 16, v52
	v_and_b32_e32 v109, 0xffff0000, v52
	v_lshlrev_b32_e32 v110, 16, v53
	v_and_b32_e32 v111, 0xffff0000, v53
	v_lshlrev_b32_e32 v112, 16, v54
	v_and_b32_e32 v113, 0xffff0000, v54
	v_lshlrev_b32_e32 v114, 16, v55
	v_and_b32_e32 v115, 0xffff0000, v55
	v_mul_f32_e32 v116, v100, v100
	v_fmac_f32_e32 v116, v101, v101
	v_fmac_f32_e32 v116, v102, v102
	v_fmac_f32_e32 v116, v103, v103
	v_fmac_f32_e32 v116, v104, v104
	v_fmac_f32_e32 v116, v105, v105
	v_fmac_f32_e32 v116, v106, v106
	v_fmac_f32_e32 v116, v107, v107
	v_fmac_f32_e32 v116, v108, v108
	v_fmac_f32_e32 v116, v109, v109
	v_fmac_f32_e32 v116, v110, v110
	v_fmac_f32_e32 v116, v111, v111
	v_fmac_f32_e32 v116, v112, v112
	v_fmac_f32_e32 v116, v113, v113
	v_fmac_f32_e32 v116, v114, v114
	v_fmac_f32_e32 v116, v115, v115
	s_nop 1
	v_add_f32_dpp v116, v116, v116 quad_perm:[1,0,3,2] row_mask:0xf bank_mask:0xf
	s_nop 1
	v_add_f32_dpp v116, v116, v116 quad_perm:[2,3,0,1] row_mask:0xf bank_mask:0xf
	s_nop 1
	v_add_f32_dpp v116, v116, v116 row_half_mirror row_mask:0xf bank_mask:0xf
	s_nop 1
	v_add_f32_dpp v116, v116, v116 row_mirror row_mask:0xf bank_mask:0xf
	s_nop 0
	v_readlane_b32 s8, v116, 0
	v_readlane_b32 s9, v116, 16
	v_readlane_b32 s10, v116, 32
	v_readlane_b32 s11, v116, 48
	s_nop 1
	v_mov_b32_e32 v117, s8
	v_add_f32_e32 v117, s9, v117
	v_add_f32_e32 v117, s10, v117
	v_add_f32_e32 v117, s11, v117
	v_fmamk_f32 v117, v117, 0x3a800000, v118
	v_rsq_f32_e32 v120, v117
	s_nop 0
	v_pk_mul_f32 v[100:101], v[100:101], v[120:121] op_sel_hi:[1,0]
	v_pk_mul_f32 v[102:103], v[102:103], v[120:121] op_sel_hi:[1,0]
	v_pk_mul_f32 v[104:105], v[104:105], v[120:121] op_sel_hi:[1,0]
	v_pk_mul_f32 v[106:107], v[106:107], v[120:121] op_sel_hi:[1,0]
	v_pk_mul_f32 v[108:109], v[108:109], v[120:121] op_sel_hi:[1,0]
	v_pk_mul_f32 v[110:111], v[110:111], v[120:121] op_sel_hi:[1,0]
	v_pk_mul_f32 v[112:113], v[112:113], v[120:121] op_sel_hi:[1,0]
	v_pk_mul_f32 v[114:115], v[114:115], v[120:121] op_sel_hi:[1,0]
	v_pk_mul_f32 v[100:101], v[100:101], v[4:5]
	v_pk_mul_f32 v[102:103], v[102:103], v[6:7]
	v_pk_mul_f32 v[104:105], v[104:105], v[8:9]
	v_pk_mul_f32 v[106:107], v[106:107], v[10:11]
	v_pk_mul_f32 v[108:109], v[108:109], v[12:13]
	v_pk_mul_f32 v[110:111], v[110:111], v[14:15]
	v_pk_mul_f32 v[112:113], v[112:113], v[16:17]
	v_pk_mul_f32 v[114:115], v[114:115], v[18:19]
	global_store_dwordx4 v3, v[100:103], s[4:5]
	global_store_dwordx4 v3, v[104:107], s[4:5] offset:1024
	global_store_dwordx4 v3, v[108:111], s[4:5] offset:2048
	global_store_dwordx4 v3, v[112:115], s[4:5] offset:3072
	s_add_u32 s4, s4, 0x1000
	s_addc_u32 s5, s5, 0
	s_nop 1
	s_waitcnt vmcnt(48)
	v_lshlrev_b32_e32 v100, 16, v56
	v_and_b32_e32 v101, 0xffff0000, v56
	v_lshlrev_b32_e32 v102, 16, v57
	v_and_b32_e32 v103, 0xffff0000, v57
	v_lshlrev_b32_e32 v104, 16, v58
	v_and_b32_e32 v105, 0xffff0000, v58
	v_lshlrev_b32_e32 v106, 16, v59
	v_and_b32_e32 v107, 0xffff0000, v59
	v_lshlrev_b32_e32 v108, 16, v60
	v_and_b32_e32 v109, 0xffff0000, v60
	v_lshlrev_b32_e32 v110, 16, v61
	v_and_b32_e32 v111, 0xffff0000, v61
	v_lshlrev_b32_e32 v112, 16, v62
	v_and_b32_e32 v113, 0xffff0000, v62
	v_lshlrev_b32_e32 v114, 16, v63
	v_and_b32_e32 v115, 0xffff0000, v63
	v_mul_f32_e32 v116, v100, v100
	v_fmac_f32_e32 v116, v101, v101
	v_fmac_f32_e32 v116, v102, v102
	v_fmac_f32_e32 v116, v103, v103
	v_fmac_f32_e32 v116, v104, v104
	v_fmac_f32_e32 v116, v105, v105
	v_fmac_f32_e32 v116, v106, v106
	v_fmac_f32_e32 v116, v107, v107
	v_fmac_f32_e32 v116, v108, v108
	v_fmac_f32_e32 v116, v109, v109
	v_fmac_f32_e32 v116, v110, v110
	v_fmac_f32_e32 v116, v111, v111
	v_fmac_f32_e32 v116, v112, v112
	v_fmac_f32_e32 v116, v113, v113
	v_fmac_f32_e32 v116, v114, v114
	v_fmac_f32_e32 v116, v115, v115
	s_nop 1
	v_add_f32_dpp v116, v116, v116 quad_perm:[1,0,3,2] row_mask:0xf bank_mask:0xf
	s_nop 1
	v_add_f32_dpp v116, v116, v116 quad_perm:[2,3,0,1] row_mask:0xf bank_mask:0xf
	s_nop 1
	v_add_f32_dpp v116, v116, v116 row_half_mirror row_mask:0xf bank_mask:0xf
	s_nop 1
	v_add_f32_dpp v116, v116, v116 row_mirror row_mask:0xf bank_mask:0xf
	s_nop 0
	v_readlane_b32 s8, v116, 0
	v_readlane_b32 s9, v116, 16
	v_readlane_b32 s10, v116, 32
	v_readlane_b32 s11, v116, 48
	s_nop 1
	v_mov_b32_e32 v117, s8
	v_add_f32_e32 v117, s9, v117
	v_add_f32_e32 v117, s10, v117
	v_add_f32_e32 v117, s11, v117
	v_fmamk_f32 v117, v117, 0x3a800000, v118
	v_rsq_f32_e32 v120, v117
	s_nop 0
	v_pk_mul_f32 v[100:101], v[100:101], v[120:121] op_sel_hi:[1,0]
	v_pk_mul_f32 v[102:103], v[102:103], v[120:121] op_sel_hi:[1,0]
	v_pk_mul_f32 v[104:105], v[104:105], v[120:121] op_sel_hi:[1,0]
	v_pk_mul_f32 v[106:107], v[106:107], v[120:121] op_sel_hi:[1,0]
	v_pk_mul_f32 v[108:109], v[108:109], v[120:121] op_sel_hi:[1,0]
	v_pk_mul_f32 v[110:111], v[110:111], v[120:121] op_sel_hi:[1,0]
	v_pk_mul_f32 v[112:113], v[112:113], v[120:121] op_sel_hi:[1,0]
	v_pk_mul_f32 v[114:115], v[114:115], v[120:121] op_sel_hi:[1,0]
	v_pk_mul_f32 v[100:101], v[100:101], v[4:5]
	v_pk_mul_f32 v[102:103], v[102:103], v[6:7]
	v_pk_mul_f32 v[104:105], v[104:105], v[8:9]
	v_pk_mul_f32 v[106:107], v[106:107], v[10:11]
	v_pk_mul_f32 v[108:109], v[108:109], v[12:13]
	v_pk_mul_f32 v[110:111], v[110:111], v[14:15]
	v_pk_mul_f32 v[112:113], v[112:113], v[16:17]
	v_pk_mul_f32 v[114:115], v[114:115], v[18:19]
	global_store_dwordx4 v3, v[100:103], s[4:5]
	global_store_dwordx4 v3, v[104:107], s[4:5] offset:1024
	global_store_dwordx4 v3, v[108:111], s[4:5] offset:2048
	global_store_dwordx4 v3, v[112:115], s[4:5] offset:3072
	s_add_u32 s4, s4, 0x1000
	s_addc_u32 s5, s5, 0
	s_nop 1
	s_waitcnt vmcnt(44)
	v_lshlrev_b32_e32 v100, 16, v64
	v_and_b32_e32 v101, 0xffff0000, v64
	v_lshlrev_b32_e32 v102, 16, v65
	v_and_b32_e32 v103, 0xffff0000, v65
	v_lshlrev_b32_e32 v104, 16, v66
	v_and_b32_e32 v105, 0xffff0000, v66
	v_lshlrev_b32_e32 v106, 16, v67
	v_and_b32_e32 v107, 0xffff0000, v67
	v_lshlrev_b32_e32 v108, 16, v68
	v_and_b32_e32 v109, 0xffff0000, v68
	v_lshlrev_b32_e32 v110, 16, v69
	v_and_b32_e32 v111, 0xffff0000, v69
	v_lshlrev_b32_e32 v112, 16, v70
	v_and_b32_e32 v113, 0xffff0000, v70
	v_lshlrev_b32_e32 v114, 16, v71
	v_and_b32_e32 v115, 0xffff0000, v71
	v_mul_f32_e32 v116, v100, v100
	v_fmac_f32_e32 v116, v101, v101
	v_fmac_f32_e32 v116, v102, v102
	v_fmac_f32_e32 v116, v103, v103
	v_fmac_f32_e32 v116, v104, v104
	v_fmac_f32_e32 v116, v105, v105
	v_fmac_f32_e32 v116, v106, v106
	v_fmac_f32_e32 v116, v107, v107
	v_fmac_f32_e32 v116, v108, v108
	v_fmac_f32_e32 v116, v109, v109
	v_fmac_f32_e32 v116, v110, v110
	v_fmac_f32_e32 v116, v111, v111
	v_fmac_f32_e32 v116, v112, v112
	v_fmac_f32_e32 v116, v113, v113
	v_fmac_f32_e32 v116, v114, v114
	v_fmac_f32_e32 v116, v115, v115
	s_nop 1
	v_add_f32_dpp v116, v116, v116 quad_perm:[1,0,3,2] row_mask:0xf bank_mask:0xf
	s_nop 1
	v_add_f32_dpp v116, v116, v116 quad_perm:[2,3,0,1] row_mask:0xf bank_mask:0xf
	s_nop 1
	v_add_f32_dpp v116, v116, v116 row_half_mirror row_mask:0xf bank_mask:0xf
	s_nop 1
	v_add_f32_dpp v116, v116, v116 row_mirror row_mask:0xf bank_mask:0xf
	s_nop 0
	v_readlane_b32 s8, v116, 0
	v_readlane_b32 s9, v116, 16
	v_readlane_b32 s10, v116, 32
	v_readlane_b32 s11, v116, 48
	s_nop 1
	v_mov_b32_e32 v117, s8
	v_add_f32_e32 v117, s9, v117
	v_add_f32_e32 v117, s10, v117
	v_add_f32_e32 v117, s11, v117
	v_fmamk_f32 v117, v117, 0x3a800000, v118
	v_rsq_f32_e32 v120, v117
	s_nop 0
	v_pk_mul_f32 v[100:101], v[100:101], v[120:121] op_sel_hi:[1,0]
	v_pk_mul_f32 v[102:103], v[102:103], v[120:121] op_sel_hi:[1,0]
	v_pk_mul_f32 v[104:105], v[104:105], v[120:121] op_sel_hi:[1,0]
	v_pk_mul_f32 v[106:107], v[106:107], v[120:121] op_sel_hi:[1,0]
	v_pk_mul_f32 v[108:109], v[108:109], v[120:121] op_sel_hi:[1,0]
	v_pk_mul_f32 v[110:111], v[110:111], v[120:121] op_sel_hi:[1,0]
	v_pk_mul_f32 v[112:113], v[112:113], v[120:121] op_sel_hi:[1,0]
	v_pk_mul_f32 v[114:115], v[114:115], v[120:121] op_sel_hi:[1,0]
	v_pk_mul_f32 v[100:101], v[100:101], v[4:5]
	v_pk_mul_f32 v[102:103], v[102:103], v[6:7]
	v_pk_mul_f32 v[104:105], v[104:105], v[8:9]
	v_pk_mul_f32 v[106:107], v[106:107], v[10:11]
	v_pk_mul_f32 v[108:109], v[108:109], v[12:13]
	v_pk_mul_f32 v[110:111], v[110:111], v[14:15]
	v_pk_mul_f32 v[112:113], v[112:113], v[16:17]
	v_pk_mul_f32 v[114:115], v[114:115], v[18:19]
	global_store_dwordx4 v3, v[100:103], s[4:5]
	global_store_dwordx4 v3, v[104:107], s[4:5] offset:1024
	global_store_dwordx4 v3, v[108:111], s[4:5] offset:2048
	global_store_dwordx4 v3, v[112:115], s[4:5] offset:3072
	s_add_u32 s4, s4, 0x1000
	s_addc_u32 s5, s5, 0
	s_nop 1
	s_waitcnt vmcnt(40)
	v_lshlrev_b32_e32 v100, 16, v72
	v_and_b32_e32 v101, 0xffff0000, v72
	v_lshlrev_b32_e32 v102, 16, v73
	v_and_b32_e32 v103, 0xffff0000, v73
	v_lshlrev_b32_e32 v104, 16, v74
	v_and_b32_e32 v105, 0xffff0000, v74
	v_lshlrev_b32_e32 v106, 16, v75
	v_and_b32_e32 v107, 0xffff0000, v75
	v_lshlrev_b32_e32 v108, 16, v76
	v_and_b32_e32 v109, 0xffff0000, v76
	v_lshlrev_b32_e32 v110, 16, v77
	v_and_b32_e32 v111, 0xffff0000, v77
	v_lshlrev_b32_e32 v112, 16, v78
	v_and_b32_e32 v113, 0xffff0000, v78
	v_lshlrev_b32_e32 v114, 16, v79
	v_and_b32_e32 v115, 0xffff0000, v79
	v_mul_f32_e32 v116, v100, v100
	v_fmac_f32_e32 v116, v101, v101
	v_fmac_f32_e32 v116, v102, v102
	v_fmac_f32_e32 v116, v103, v103
	v_fmac_f32_e32 v116, v104, v104
	v_fmac_f32_e32 v116, v105, v105
	v_fmac_f32_e32 v116, v106, v106
	v_fmac_f32_e32 v116, v107, v107
	v_fmac_f32_e32 v116, v108, v108
	v_fmac_f32_e32 v116, v109, v109
	v_fmac_f32_e32 v116, v110, v110
	v_fmac_f32_e32 v116, v111, v111
	v_fmac_f32_e32 v116, v112, v112
	v_fmac_f32_e32 v116, v113, v113
	v_fmac_f32_e32 v116, v114, v114
	v_fmac_f32_e32 v116, v115, v115
	s_nop 1
	v_add_f32_dpp v116, v116, v116 quad_perm:[1,0,3,2] row_mask:0xf bank_mask:0xf
	s_nop 1
	v_add_f32_dpp v116, v116, v116 quad_perm:[2,3,0,1] row_mask:0xf bank_mask:0xf
	s_nop 1
	v_add_f32_dpp v116, v116, v116 row_half_mirror row_mask:0xf bank_mask:0xf
	s_nop 1
	v_add_f32_dpp v116, v116, v116 row_mirror row_mask:0xf bank_mask:0xf
	s_nop 0
	v_readlane_b32 s8, v116, 0
	v_readlane_b32 s9, v116, 16
	v_readlane_b32 s10, v116, 32
	v_readlane_b32 s11, v116, 48
	s_nop 1
	v_mov_b32_e32 v117, s8
	v_add_f32_e32 v117, s9, v117
	v_add_f32_e32 v117, s10, v117
	v_add_f32_e32 v117, s11, v117
	v_fmamk_f32 v117, v117, 0x3a800000, v118
	v_rsq_f32_e32 v120, v117
	s_nop 0
	v_pk_mul_f32 v[100:101], v[100:101], v[120:121] op_sel_hi:[1,0]
	v_pk_mul_f32 v[102:103], v[102:103], v[120:121] op_sel_hi:[1,0]
	v_pk_mul_f32 v[104:105], v[104:105], v[120:121] op_sel_hi:[1,0]
	v_pk_mul_f32 v[106:107], v[106:107], v[120:121] op_sel_hi:[1,0]
	v_pk_mul_f32 v[108:109], v[108:109], v[120:121] op_sel_hi:[1,0]
	v_pk_mul_f32 v[110:111], v[110:111], v[120:121] op_sel_hi:[1,0]
	v_pk_mul_f32 v[112:113], v[112:113], v[120:121] op_sel_hi:[1,0]
	v_pk_mul_f32 v[114:115], v[114:115], v[120:121] op_sel_hi:[1,0]
	v_pk_mul_f32 v[100:101], v[100:101], v[4:5]
	v_pk_mul_f32 v[102:103], v[102:103], v[6:7]
	v_pk_mul_f32 v[104:105], v[104:105], v[8:9]
	v_pk_mul_f32 v[106:107], v[106:107], v[10:11]
	v_pk_mul_f32 v[108:109], v[108:109], v[12:13]
	v_pk_mul_f32 v[110:111], v[110:111], v[14:15]
	v_pk_mul_f32 v[112:113], v[112:113], v[16:17]
	v_pk_mul_f32 v[114:115], v[114:115], v[18:19]
	global_store_dwordx4 v3, v[100:103], s[4:5]
	global_store_dwordx4 v3, v[104:107], s[4:5] offset:1024
	global_store_dwordx4 v3, v[108:111], s[4:5] offset:2048
	global_store_dwordx4 v3, v[112:115], s[4:5] offset:3072
	s_add_u32 s4, s4, 0x1000
	s_addc_u32 s5, s5, 0
	s_nop 1
	s_waitcnt vmcnt(36)
	v_lshlrev_b32_e32 v100, 16, v80
	v_and_b32_e32 v101, 0xffff0000, v80
	v_lshlrev_b32_e32 v102, 16, v81
	v_and_b32_e32 v103, 0xffff0000, v81
	v_lshlrev_b32_e32 v104, 16, v82
	v_and_b32_e32 v105, 0xffff0000, v82
	v_lshlrev_b32_e32 v106, 16, v83
	v_and_b32_e32 v107, 0xffff0000, v83
	v_lshlrev_b32_e32 v108, 16, v84
	v_and_b32_e32 v109, 0xffff0000, v84
	v_lshlrev_b32_e32 v110, 16, v85
	v_and_b32_e32 v111, 0xffff0000, v85
	v_lshlrev_b32_e32 v112, 16, v86
	v_and_b32_e32 v113, 0xffff0000, v86
	v_lshlrev_b32_e32 v114, 16, v87
	v_and_b32_e32 v115, 0xffff0000, v87
	v_mul_f32_e32 v116, v100, v100
	v_fmac_f32_e32 v116, v101, v101
	v_fmac_f32_e32 v116, v102, v102
	v_fmac_f32_e32 v116, v103, v103
	v_fmac_f32_e32 v116, v104, v104
	v_fmac_f32_e32 v116, v105, v105
	v_fmac_f32_e32 v116, v106, v106
	v_fmac_f32_e32 v116, v107, v107
	v_fmac_f32_e32 v116, v108, v108
	v_fmac_f32_e32 v116, v109, v109
	v_fmac_f32_e32 v116, v110, v110
	v_fmac_f32_e32 v116, v111, v111
	v_fmac_f32_e32 v116, v112, v112
	v_fmac_f32_e32 v116, v113, v113
	v_fmac_f32_e32 v116, v114, v114
	v_fmac_f32_e32 v116, v115, v115
	s_nop 1
	v_add_f32_dpp v116, v116, v116 quad_perm:[1,0,3,2] row_mask:0xf bank_mask:0xf
	s_nop 1
	v_add_f32_dpp v116, v116, v116 quad_perm:[2,3,0,1] row_mask:0xf bank_mask:0xf
	s_nop 1
	v_add_f32_dpp v116, v116, v116 row_half_mirror row_mask:0xf bank_mask:0xf
	s_nop 1
	v_add_f32_dpp v116, v116, v116 row_mirror row_mask:0xf bank_mask:0xf
	s_nop 0
	v_readlane_b32 s8, v116, 0
	v_readlane_b32 s9, v116, 16
	v_readlane_b32 s10, v116, 32
	v_readlane_b32 s11, v116, 48
	s_nop 1
	v_mov_b32_e32 v117, s8
	v_add_f32_e32 v117, s9, v117
	v_add_f32_e32 v117, s10, v117
	v_add_f32_e32 v117, s11, v117
	v_fmamk_f32 v117, v117, 0x3a800000, v118
	v_rsq_f32_e32 v120, v117
	s_nop 0
	v_pk_mul_f32 v[100:101], v[100:101], v[120:121] op_sel_hi:[1,0]
	v_pk_mul_f32 v[102:103], v[102:103], v[120:121] op_sel_hi:[1,0]
	v_pk_mul_f32 v[104:105], v[104:105], v[120:121] op_sel_hi:[1,0]
	v_pk_mul_f32 v[106:107], v[106:107], v[120:121] op_sel_hi:[1,0]
	v_pk_mul_f32 v[108:109], v[108:109], v[120:121] op_sel_hi:[1,0]
	v_pk_mul_f32 v[110:111], v[110:111], v[120:121] op_sel_hi:[1,0]
	v_pk_mul_f32 v[112:113], v[112:113], v[120:121] op_sel_hi:[1,0]
	v_pk_mul_f32 v[114:115], v[114:115], v[120:121] op_sel_hi:[1,0]
	v_pk_mul_f32 v[100:101], v[100:101], v[4:5]
	v_pk_mul_f32 v[102:103], v[102:103], v[6:7]
	v_pk_mul_f32 v[104:105], v[104:105], v[8:9]
	v_pk_mul_f32 v[106:107], v[106:107], v[10:11]
	v_pk_mul_f32 v[108:109], v[108:109], v[12:13]
	v_pk_mul_f32 v[110:111], v[110:111], v[14:15]
	v_pk_mul_f32 v[112:113], v[112:113], v[16:17]
	v_pk_mul_f32 v[114:115], v[114:115], v[18:19]
	global_store_dwordx4 v3, v[100:103], s[4:5]
	global_store_dwordx4 v3, v[104:107], s[4:5] offset:1024
	global_store_dwordx4 v3, v[108:111], s[4:5] offset:2048
	global_store_dwordx4 v3, v[112:115], s[4:5] offset:3072
	s_add_u32 s4, s4, 0x1000
	s_addc_u32 s5, s5, 0
	s_nop 1
	s_waitcnt vmcnt(32)
	v_lshlrev_b32_e32 v100, 16, v88
	v_and_b32_e32 v101, 0xffff0000, v88
	v_lshlrev_b32_e32 v102, 16, v89
	v_and_b32_e32 v103, 0xffff0000, v89
	v_lshlrev_b32_e32 v104, 16, v90
	v_and_b32_e32 v105, 0xffff0000, v90
	v_lshlrev_b32_e32 v106, 16, v91
	v_and_b32_e32 v107, 0xffff0000, v91
	v_lshlrev_b32_e32 v108, 16, v92
	v_and_b32_e32 v109, 0xffff0000, v92
	v_lshlrev_b32_e32 v110, 16, v93
	v_and_b32_e32 v111, 0xffff0000, v93
	v_lshlrev_b32_e32 v112, 16, v94
	v_and_b32_e32 v113, 0xffff0000, v94
	v_lshlrev_b32_e32 v114, 16, v95
	v_and_b32_e32 v115, 0xffff0000, v95
	v_mul_f32_e32 v116, v100, v100
	v_fmac_f32_e32 v116, v101, v101
	v_fmac_f32_e32 v116, v102, v102
	v_fmac_f32_e32 v116, v103, v103
	v_fmac_f32_e32 v116, v104, v104
	v_fmac_f32_e32 v116, v105, v105
	v_fmac_f32_e32 v116, v106, v106
	v_fmac_f32_e32 v116, v107, v107
	v_fmac_f32_e32 v116, v108, v108
	v_fmac_f32_e32 v116, v109, v109
	v_fmac_f32_e32 v116, v110, v110
	v_fmac_f32_e32 v116, v111, v111
	v_fmac_f32_e32 v116, v112, v112
	v_fmac_f32_e32 v116, v113, v113
	v_fmac_f32_e32 v116, v114, v114
	v_fmac_f32_e32 v116, v115, v115
	s_nop 1
	v_add_f32_dpp v116, v116, v116 quad_perm:[1,0,3,2] row_mask:0xf bank_mask:0xf
	s_nop 1
	v_add_f32_dpp v116, v116, v116 quad_perm:[2,3,0,1] row_mask:0xf bank_mask:0xf
	s_nop 1
	v_add_f32_dpp v116, v116, v116 row_half_mirror row_mask:0xf bank_mask:0xf
	s_nop 1
	v_add_f32_dpp v116, v116, v116 row_mirror row_mask:0xf bank_mask:0xf
	s_nop 0
	v_readlane_b32 s8, v116, 0
	v_readlane_b32 s9, v116, 16
	v_readlane_b32 s10, v116, 32
	v_readlane_b32 s11, v116, 48
	s_nop 1
	v_mov_b32_e32 v117, s8
	v_add_f32_e32 v117, s9, v117
	v_add_f32_e32 v117, s10, v117
	v_add_f32_e32 v117, s11, v117
	v_fmamk_f32 v117, v117, 0x3a800000, v118
	v_rsq_f32_e32 v120, v117
	s_nop 0
	v_pk_mul_f32 v[100:101], v[100:101], v[120:121] op_sel_hi:[1,0]
	v_pk_mul_f32 v[102:103], v[102:103], v[120:121] op_sel_hi:[1,0]
	v_pk_mul_f32 v[104:105], v[104:105], v[120:121] op_sel_hi:[1,0]
	v_pk_mul_f32 v[106:107], v[106:107], v[120:121] op_sel_hi:[1,0]
	v_pk_mul_f32 v[108:109], v[108:109], v[120:121] op_sel_hi:[1,0]
	v_pk_mul_f32 v[110:111], v[110:111], v[120:121] op_sel_hi:[1,0]
	v_pk_mul_f32 v[112:113], v[112:113], v[120:121] op_sel_hi:[1,0]
	v_pk_mul_f32 v[114:115], v[114:115], v[120:121] op_sel_hi:[1,0]
	v_pk_mul_f32 v[100:101], v[100:101], v[4:5]
	v_pk_mul_f32 v[102:103], v[102:103], v[6:7]
	v_pk_mul_f32 v[104:105], v[104:105], v[8:9]
	v_pk_mul_f32 v[106:107], v[106:107], v[10:11]
	v_pk_mul_f32 v[108:109], v[108:109], v[12:13]
	v_pk_mul_f32 v[110:111], v[110:111], v[14:15]
	v_pk_mul_f32 v[112:113], v[112:113], v[16:17]
	v_pk_mul_f32 v[114:115], v[114:115], v[18:19]
	global_store_dwordx4 v3, v[100:103], s[4:5]
	global_store_dwordx4 v3, v[104:107], s[4:5] offset:1024
	global_store_dwordx4 v3, v[108:111], s[4:5] offset:2048
	global_store_dwordx4 v3, v[112:115], s[4:5] offset:3072
	s_add_u32 s4, s4, 0x1000
	s_addc_u32 s5, s5, 0
	s_nop 1
